# PH5 rwkv_out loop software-pipelined by one iteration (two register sets; next iteration's 6 loads issued before this iteration's group-norm arithmetic)
# baseline (speedup 1.0000x reference)
; __device__ __forceinline__ f32x4 bf4(u32x2 w) { return (f32x4){bflo(w.x), bfhi(w.x), bflo(w.y), bfhi(w.y)}; }
; __device__ __forceinline__ void rwkv_out_phase(int nrows, const bf16* Y, const bf16* G, const bf16* BV, const float* gng, const float* gnb, bf16* CC, int tid) {
;     const int l16 = tid & 15;
;     for (int gi = (blockIdx.x * NTHR + tid) >> 4; gi < nrows * NH; gi += (gridDim.x * NTHR) >> 4) {
;         const int m = gi / NH, h = gi % NH; int b, s;
;         if (m < ML) { b = m >> 13; s = CTXL + (m & 8191); } else { b = (m - ML) >> 8; s = (m - ML) & 255; }
;         const int c = h * 64 + 4 * l16;
;         const f32x4 y0 = bf4(*(const u32x2*)(Y + ((size_t)(b * SL + s)) * BW + c)), y1 = bf4(*(const u32x2*)(Y + ((size_t)((2 + b) * SL + s)) * BW + c));
.LBB0_630:
	s_cmp_lt_i32 s72, 6
	s_cselect_b64 s[0:1], -1, 0
	s_cmp_gt_i32 s73, 5
	s_cselect_b64 s[4:5], -1, 0
	s_and_b64 s[0:1], s[0:1], s[4:5]
	s_andn2_b64 vcc, exec, s[0:1]
	v_readlane_b32 s0, v246, 0
	s_nop 1
	v_lshl_add_u32 v175, s0, 9, v174
	s_cbranch_vccnz .LBB0_692
	v_readlane_b32 s0, v246, 0
	s_nop 1
	v_lshl_add_u32 v0, s0, 9, v174
	s_mov_b32 s0, 0x318000
	v_cmp_gt_u32_e32 vcc, s0, v0
	s_and_saveexec_b64 s[0:1], vcc
	s_cbranch_execz .LBB0_638
	v_mbcnt_lo_u32_b32 v1, -1, 0
	v_mbcnt_hi_u32_b32 v1, -1, v1
	v_and_b32_e32 v2, 64, v1
	v_add_u32_e32 v2, 64, v2
	v_xor_b32_e32 v3, 1, v1
	v_cmp_lt_i32_e32 vcc, v3, v2
	s_add_u32 s8, s70, 0x24e00000
	s_addc_u32 s9, s71, 0
	v_cndmask_b32_e32 v3, v1, v3, vcc
	s_waitcnt vmcnt(3)
	v_lshlrev_b32_e32 v11, 2, v3
	v_xor_b32_e32 v3, 2, v1
	v_cmp_lt_i32_e32 vcc, v3, v2
	s_add_u32 s34, s70, 0x28000000
	s_addc_u32 s35, s71, 0
	v_cndmask_b32_e32 v3, v1, v3, vcc
	s_waitcnt vmcnt(2)
	v_lshlrev_b32_e32 v12, 2, v3
	v_xor_b32_e32 v3, 4, v1
	v_cmp_lt_i32_e32 vcc, v3, v2
	s_add_u32 s52, s70, 0x29900000
	v_lshrrev_b32_e32 v10, 4, v0
	v_cndmask_b32_e32 v3, v1, v3, vcc
	v_lshlrev_b32_e32 v13, 2, v3
	v_xor_b32_e32 v3, 8, v1
	v_lshlrev_b32_e32 v0, 2, v174
	v_cmp_lt_i32_e32 vcc, v3, v2
	s_addc_u32 s53, s71, 0
	v_and_b32_e32 v0, 60, v0
	s_lshl_b32 s3, s74, 5
	v_cndmask_b32_e32 v1, v1, v3, vcc
	s_and_b32 s3, s3, 0xfffffe0
	v_lshlrev_b32_e32 v14, 2, v1
	v_lshl_or_b32 v15, v10, 6, v0
	s_lshl_b32 s6, s74, 11
	s_mov_b64 s[4:5], 0
	s_mov_b32 s7, 0xaaaaaaab
	s_mov_b32 s10, 0x2ffff
	s_movk_i32 s11, 0x300
	s_movk_i32 s28, 0x2100
	s_movk_i32 s29, 0x600
	v_mov_b64_e32 v[0:1], s[8:9]
	v_mov_b32_e32 v3, 0
	s_mov_b32 s30, 0xffff0000
	s_waitcnt vmcnt(1)
	v_mov_b32_e32 v16, 0x3a27c5ac
	s_mov_b32 s31, 0x800000
	v_mov_b64_e32 v[4:5], s[52:53]
	v_mov_b64_e32 v[6:7], s[34:35]
	s_movk_i32 s33, 0x7fff
	s_mov_b32 s34, 0x317ff
	v_mov_b32_e32 v43, v3
	v_mul_hi_u32 v2, v10, s7
	v_lshrrev_b32_e32 v8, 3, v2
	v_cmp_lt_u32_e32 vcc, s10, v10
	s_and_saveexec_b64 s[8:9], vcc
	s_xor_b64 s[8:9], exec, s[8:9]
	v_add_u32_e32 v2, 0xffffc000, v8
	v_lshrrev_b32_e32 v9, 8, v2
	v_and_b32_e32 v17, 0xff, v8
	s_andn2_saveexec_b64 s[8:9], s[8:9]
	v_and_b32_e32 v2, 0x1fff, v8
	v_lshrrev_b32_e32 v9, 13, v8
	v_add_u32_e32 v17, 0x100, v2
	s_or_b64 exec, exec, s[8:9]
	v_mul_lo_u32 v2, v8, s11
	v_sub_u32_e32 v2, v15, v2
	v_mad_u32_u24 v9, v9, s28, v17
	v_mad_u64_u32 v[18:19], s[8:9], v9, s29, v[0:1]
	v_lshlrev_b64 v[26:27], 1, v[2:3]
	v_lshl_add_u64 v[18:19], v[18:19], 0, v[26:27]
	v_add_u32_e32 v9, 0x4200, v9
	global_load_dwordx2 v[28:29], v[18:19], off
	v_mad_i64_i32 v[18:19], s[8:9], v9, s29, v[0:1]
	v_lshl_add_u64 v[18:19], v[18:19], 0, v[26:27]
	global_load_dwordx2 v[30:31], v[18:19], off
	v_mad_u64_u32 v[18:19], s[8:9], v8, s29, v[4:5]
	v_lshl_add_u64 v[18:19], v[18:19], 0, v[26:27]
	global_load_dwordx2 v[32:33], v[18:19], off
	v_mad_u64_u32 v[18:19], s[8:9], v8, s29, v[6:7]
	v_lshl_add_u64 v[18:19], v[18:19], 0, v[26:27]
	v_readlane_b32 s12, v246, 39
	global_load_dwordx2 v[34:35], v[18:19], off
	v_lshlrev_b64 v[18:19], 2, v[2:3]
	v_readlane_b32 s16, v246, 43
	v_readlane_b32 s17, v246, 44
	v_readlane_b32 s18, v246, 45
	v_readlane_b32 s19, v246, 46
	s_waitcnt vmcnt(4)
	v_lshl_add_u64 v[20:21], s[16:17], 0, v[18:19]
	v_add_u32_e32 v10, s3, v10
	v_lshl_add_u64 v[22:23], s[18:19], 0, v[18:19]
	global_load_dwordx4 v[18:21], v[20:21], off
	s_nop 0
	global_load_dwordx4 v[22:25], v[22:23], off
	v_cmp_lt_u32_e32 vcc, s34, v10
	s_or_b64 s[4:5], vcc, s[4:5]
	v_add_u32_e32 v15, s6, v15
	v_readlane_b32 s13, v246, 40
	v_readlane_b32 s14, v246, 41
	v_readlane_b32 s15, v246, 42
	v_readlane_b32 s20, v246, 47
	v_readlane_b32 s21, v246, 48
	v_readlane_b32 s22, v246, 49
	v_readlane_b32 s23, v246, 50
	v_readlane_b32 s24, v246, 51
	v_readlane_b32 s25, v246, 52
	v_readlane_b32 s26, v246, 53
	v_readlane_b32 s27, v246, 54
.Lpo5_loopx:
	s_mov_b64 s[92:93], exec
	s_andn2_b64 exec, exec, s[4:5]
	s_cbranch_execz .Lpo5_drainx
	s_mov_b64 s[94:95], exec
	v_mul_hi_u32 v42, v10, s7
	v_lshrrev_b32_e32 v48, 3, v42
	v_cmp_lt_u32_e32 vcc, s10, v10
	s_and_saveexec_b64 s[8:9], vcc
	s_xor_b64 s[8:9], exec, s[8:9]
	v_add_u32_e32 v42, 0xffffc000, v48
	v_lshrrev_b32_e32 v49, 8, v42
	v_and_b32_e32 v57, 0xff, v48
	s_andn2_saveexec_b64 s[8:9], s[8:9]
	v_and_b32_e32 v42, 0x1fff, v48
	v_lshrrev_b32_e32 v49, 13, v48
	v_add_u32_e32 v57, 0x100, v42
	s_or_b64 exec, exec, s[8:9]
	v_mul_lo_u32 v42, v48, s11
	v_sub_u32_e32 v42, v15, v42
	v_mad_u32_u24 v49, v49, s28, v57
	v_mad_u64_u32 v[58:59], s[8:9], v49, s29, v[0:1]
	v_lshlrev_b64 v[66:67], 1, v[42:43]
	v_lshl_add_u64 v[58:59], v[58:59], 0, v[66:67]
	v_add_u32_e32 v49, 0x4200, v49
	global_load_dwordx2 v[68:69], v[58:59], off
	v_mad_i64_i32 v[58:59], s[8:9], v49, s29, v[0:1]
	v_lshl_add_u64 v[58:59], v[58:59], 0, v[66:67]
	global_load_dwordx2 v[70:71], v[58:59], off
	v_mad_u64_u32 v[58:59], s[8:9], v48, s29, v[4:5]
	v_lshl_add_u64 v[58:59], v[58:59], 0, v[66:67]
	global_load_dwordx2 v[72:73], v[58:59], off
	v_mad_u64_u32 v[58:59], s[8:9], v48, s29, v[6:7]
	v_lshl_add_u64 v[58:59], v[58:59], 0, v[66:67]
	v_readlane_b32 s12, v246, 39
	global_load_dwordx2 v[74:75], v[58:59], off
	v_lshlrev_b64 v[58:59], 2, v[42:43]
	v_readlane_b32 s16, v246, 43
	v_readlane_b32 s17, v246, 44
	v_readlane_b32 s18, v246, 45
	v_readlane_b32 s19, v246, 46
	s_waitcnt vmcnt(4)
; __device__ __forceinline__ unsigned pk2(float lo, float hi) { return f2bf(lo) | (f2bf(hi) << 16); }
; __device__ __forceinline__ f32x4 bf4(u32x2 w) { return (f32x4){bflo(w.x), bfhi(w.x), bflo(w.y), bfhi(w.y)}; }
; __device__ __forceinline__ void rwkv_out_phase(int nrows, const bf16* Y, const bf16* G, const bf16* BV, const float* gng, const float* gnb, bf16* CC, int tid) {
;     ...
;         const f32x4 y0 = bf4(*(const u32x2*)(Y + ((size_t)(b * SL + s)) * BW + c)), y1 = bf4(*(const u32x2*)(Y + ((size_t)((2 + b) * SL + s)) * BW + c));
;         f32x4 y = y0 + y1;
;         float sm = (y.x + y.y) + (y.z + y.w);
; #pragma unroll
;         for (int o = 1; o < 16; o <<= 1) sm += __shfl_xor(sm, o);
;         const float mu = sm * (1.f / 64.f); y = y - mu;
;         float s2 = (y.x * y.x + y.y * y.y) + (y.z * y.z + y.w * y.w);
; #pragma unroll
;         for (int o = 1; o < 16; o <<= 1) s2 += __shfl_xor(s2, o);
;         const float rstd = rsqrtf(s2 * (1.f / 64.f) + GN_EPS);
;         const f32x4 gg = *(const f32x4*)(gng + c), gb = *(const f32x4*)(gnb + c);
;         const f32x4 bv = bf4(*(const u32x2*)(BV + (size_t)m * BW + c)), gt = bf4(*(const u32x2*)(G + (size_t)m * BW + c));
;         const f32x4 o = (y * rstd * gg + gb + bv) * gt;
;         u32x2 w; w.x = pk2(o.x, o.y); w.y = pk2(o.z, o.w);
;         *(u32x2*)(CC + (size_t)m * D + 512 + c) = w;
	v_lshl_add_u64 v[60:61], s[16:17], 0, v[58:59]
	v_add_u32_e32 v10, s3, v10
	v_lshl_add_u64 v[62:63], s[18:19], 0, v[58:59]
	global_load_dwordx4 v[58:61], v[60:61], off
	s_nop 0
	global_load_dwordx4 v[62:65], v[62:63], off
	v_cmp_lt_u32_e32 vcc, s34, v10
	s_or_b64 s[4:5], vcc, s[4:5]
	v_add_u32_e32 v15, s6, v15
	v_readlane_b32 s13, v246, 40
	v_readlane_b32 s14, v246, 41
	v_readlane_b32 s15, v246, 42
	v_readlane_b32 s20, v246, 47
	v_readlane_b32 s21, v246, 48
	v_readlane_b32 s22, v246, 49
	v_readlane_b32 s23, v246, 50
	v_readlane_b32 s24, v246, 51
	v_readlane_b32 s25, v246, 52
	v_readlane_b32 s26, v246, 53
	v_readlane_b32 s27, v246, 54
	s_mov_b64 exec, s[92:93]
	s_waitcnt vmcnt(11)
	v_lshlrev_b32_e32 v36, 16, v28
	v_and_b32_e32 v37, 0xffff0000, v28
	v_lshlrev_b32_e32 v28, 16, v29
	v_and_b32_e32 v29, 0xffff0000, v29
	s_waitcnt vmcnt(10)
	v_lshlrev_b32_e32 v38, 16, v30
	v_and_b32_e32 v39, 0xffff0000, v30
	v_lshlrev_b32_e32 v30, 16, v31
	v_and_b32_e32 v31, 0xffff0000, v31
	v_pk_add_f32 v[28:29], v[28:29], v[30:31]
	v_pk_add_f32 v[30:31], v[36:37], v[38:39]
	v_mov_b32_e32 v39, v29
	v_pk_mov_b32 v[36:37], v[30:31], v[28:29] op_sel:[1,0]
	v_mov_b32_e32 v38, v30
	v_pk_add_f32 v[36:37], v[36:37], v[38:39]
	s_nop 0
	v_add_f32_e32 v2, v36, v37
	ds_bpermute_b32 v9, v11, v2
	s_waitcnt lgkmcnt(0)
	v_add_f32_e32 v2, v2, v9
	ds_bpermute_b32 v9, v12, v2
	s_waitcnt lgkmcnt(0)
	v_add_f32_e32 v2, v2, v9
	ds_bpermute_b32 v9, v13, v2
	s_waitcnt lgkmcnt(0)
	v_add_f32_e32 v2, v2, v9
	ds_bpermute_b32 v17, v14, v2
	v_mov_b32_e32 v9, v3
	v_lshlrev_b64 v[8:9], 12, v[8:9]
	v_lshl_add_u64 v[8:9], s[70:71], 0, v[8:9]
	v_lshl_add_u64 v[8:9], v[8:9], 0, v[26:27]
	s_waitcnt lgkmcnt(0)
	v_add_f32_e32 v2, v2, v17
	v_fmamk_f32 v31, v2, 0xbc800000, v31
	v_fmac_f32_e32 v30, 0xbc800000, v2
	v_fmamk_f32 v29, v2, 0xbc800000, v29
	v_fmac_f32_e32 v28, 0xbc800000, v2
	v_pk_mul_f32 v[36:37], v[28:29], v[28:29]
	v_pk_mul_f32 v[38:39], v[30:31], v[30:31]
	v_add_co_u32_e32 v8, vcc, 0x6700000, v8
	v_pk_mov_b32 v[40:41], v[38:39], v[36:37] op_sel:[1,0]
	v_mov_b32_e32 v39, v37
	v_pk_add_f32 v[36:37], v[40:41], v[38:39]
	v_addc_co_u32_e32 v9, vcc, 0, v9, vcc
	v_add_f32_e32 v2, v36, v37
	ds_bpermute_b32 v17, v11, v2
	s_waitcnt vmcnt(9)
	v_lshlrev_b32_e32 v26, 16, v32
	v_and_b32_e32 v27, 0xffff0000, v32
	v_lshlrev_b32_e32 v32, 16, v33
	v_and_b32_e32 v33, 0xffff0000, v33
	s_waitcnt lgkmcnt(0)
	v_add_f32_e32 v2, v2, v17
	ds_bpermute_b32 v17, v12, v2
	s_waitcnt vmcnt(8)
	v_lshlrev_b32_e32 v36, 16, v34
	v_and_b32_e32 v37, 0xffff0000, v34
	v_lshlrev_b32_e32 v34, 16, v35
	v_and_b32_e32 v35, 0xffff0000, v35
	s_waitcnt lgkmcnt(0)
	v_add_f32_e32 v2, v2, v17
	ds_bpermute_b32 v17, v13, v2
	s_waitcnt lgkmcnt(0)
	v_add_f32_e32 v2, v2, v17
	ds_bpermute_b32 v17, v14, v2
	s_waitcnt lgkmcnt(0)
	v_add_f32_e32 v2, v2, v17
	v_fmamk_f32 v2, v2, 0x3c800000, v16
	v_mul_f32_e32 v17, 0x4b800000, v2
	v_cmp_gt_f32_e32 vcc, s31, v2
	s_nop 1
	v_cndmask_b32_e32 v2, v2, v17, vcc
	v_rsq_f32_e32 v2, v2
	s_nop 0
	v_mul_f32_e32 v17, 0x45800000, v2
	v_cndmask_b32_e32 v2, v2, v17, vcc
	v_pk_mul_f32 v[30:31], v[30:31], v[2:3] op_sel_hi:[1,0]
	v_pk_mul_f32 v[28:29], v[28:29], v[2:3] op_sel_hi:[1,0]
	s_waitcnt vmcnt(6)
	v_pk_fma_f32 v[18:19], v[18:19], v[30:31], v[22:23]
	v_pk_fma_f32 v[20:21], v[20:21], v[28:29], v[24:25]
	v_pk_add_f32 v[18:19], v[18:19], v[26:27]
	v_pk_add_f32 v[20:21], v[20:21], v[32:33]
	v_pk_mul_f32 v[18:19], v[18:19], v[36:37]
	v_pk_mul_f32 v[20:21], v[20:21], v[34:35]
	v_bfe_u32 v2, v18, 16, 1
	v_bfe_u32 v22, v20, 16, 1
	v_bfe_u32 v17, v19, 16, 1
	v_bfe_u32 v23, v21, 16, 1
	v_add3_u32 v2, v18, v2, s33
	v_add3_u32 v18, v20, v22, s33
	v_add3_u32 v17, v19, v17, s33
	v_add3_u32 v19, v21, v23, s33
	v_lshrrev_b32_e32 v2, 16, v2
	v_lshrrev_b32_e32 v20, 16, v18
	v_and_or_b32 v18, v17, s30, v2
	v_and_or_b32 v19, v19, s30, v20
	global_store_dwordx2 v[8:9], v[18:19], off offset:1024
	s_mov_b64 exec, s[94:95]
	s_mov_b64 s[92:93], exec
	s_andn2_b64 exec, exec, s[4:5]
	s_cbranch_execz .Lpo5_drainy
	s_mov_b64 s[94:95], exec
	v_mul_hi_u32 v2, v10, s7
	v_lshrrev_b32_e32 v8, 3, v2
	v_cmp_lt_u32_e32 vcc, s10, v10
	s_and_saveexec_b64 s[8:9], vcc
	s_xor_b64 s[8:9], exec, s[8:9]
	v_add_u32_e32 v2, 0xffffc000, v8
	v_lshrrev_b32_e32 v9, 8, v2
	v_and_b32_e32 v17, 0xff, v8
	s_andn2_saveexec_b64 s[8:9], s[8:9]
	v_and_b32_e32 v2, 0x1fff, v8
	v_lshrrev_b32_e32 v9, 13, v8
	v_add_u32_e32 v17, 0x100, v2
	s_or_b64 exec, exec, s[8:9]
	v_mul_lo_u32 v2, v8, s11
	v_sub_u32_e32 v2, v15, v2
	v_mad_u32_u24 v9, v9, s28, v17
	v_mad_u64_u32 v[18:19], s[8:9], v9, s29, v[0:1]
	v_lshlrev_b64 v[26:27], 1, v[2:3]
	v_lshl_add_u64 v[18:19], v[18:19], 0, v[26:27]
	v_add_u32_e32 v9, 0x4200, v9
	global_load_dwordx2 v[28:29], v[18:19], off
	v_mad_i64_i32 v[18:19], s[8:9], v9, s29, v[0:1]
	v_lshl_add_u64 v[18:19], v[18:19], 0, v[26:27]
	global_load_dwordx2 v[30:31], v[18:19], off
	v_mad_u64_u32 v[18:19], s[8:9], v8, s29, v[4:5]
	v_lshl_add_u64 v[18:19], v[18:19], 0, v[26:27]
	global_load_dwordx2 v[32:33], v[18:19], off
	v_mad_u64_u32 v[18:19], s[8:9], v8, s29, v[6:7]
	v_lshl_add_u64 v[18:19], v[18:19], 0, v[26:27]
	v_readlane_b32 s12, v246, 39
	global_load_dwordx2 v[34:35], v[18:19], off
	v_lshlrev_b64 v[18:19], 2, v[2:3]
	v_readlane_b32 s16, v246, 43
	v_readlane_b32 s17, v246, 44
	v_readlane_b32 s18, v246, 45
	v_readlane_b32 s19, v246, 46
	s_waitcnt vmcnt(4)
; __device__ __forceinline__ unsigned pk2(float lo, float hi) { return f2bf(lo) | (f2bf(hi) << 16); }
; __device__ __forceinline__ f32x4 bf4(u32x2 w) { return (f32x4){bflo(w.x), bfhi(w.x), bflo(w.y), bfhi(w.y)}; }
; __device__ __forceinline__ void rwkv_out_phase(int nrows, const bf16* Y, const bf16* G, const bf16* BV, const float* gng, const float* gnb, bf16* CC, int tid) {
;     ...
;         const f32x4 y0 = bf4(*(const u32x2*)(Y + ((size_t)(b * SL + s)) * BW + c)), y1 = bf4(*(const u32x2*)(Y + ((size_t)((2 + b) * SL + s)) * BW + c));
;         f32x4 y = y0 + y1;
;         float sm = (y.x + y.y) + (y.z + y.w);
; #pragma unroll
;         for (int o = 1; o < 16; o <<= 1) sm += __shfl_xor(sm, o);
;         const float mu = sm * (1.f / 64.f); y = y - mu;
;         float s2 = (y.x * y.x + y.y * y.y) + (y.z * y.z + y.w * y.w);
; #pragma unroll
;         for (int o = 1; o < 16; o <<= 1) s2 += __shfl_xor(s2, o);
;         const float rstd = rsqrtf(s2 * (1.f / 64.f) + GN_EPS);
;         const f32x4 gg = *(const f32x4*)(gng + c), gb = *(const f32x4*)(gnb + c);
;         const f32x4 bv = bf4(*(const u32x2*)(BV + (size_t)m * BW + c)), gt = bf4(*(const u32x2*)(G + (size_t)m * BW + c));
;         const f32x4 o = (y * rstd * gg + gb + bv) * gt;
;         u32x2 w; w.x = pk2(o.x, o.y); w.y = pk2(o.z, o.w);
;         *(u32x2*)(CC + (size_t)m * D + 512 + c) = w;
	v_lshl_add_u64 v[20:21], s[16:17], 0, v[18:19]
	v_add_u32_e32 v10, s3, v10
	v_lshl_add_u64 v[22:23], s[18:19], 0, v[18:19]
	global_load_dwordx4 v[18:21], v[20:21], off
	s_nop 0
	global_load_dwordx4 v[22:25], v[22:23], off
	v_cmp_lt_u32_e32 vcc, s34, v10
	s_or_b64 s[4:5], vcc, s[4:5]
	v_add_u32_e32 v15, s6, v15
	v_readlane_b32 s13, v246, 40
	v_readlane_b32 s14, v246, 41
	v_readlane_b32 s15, v246, 42
	v_readlane_b32 s20, v246, 47
	v_readlane_b32 s21, v246, 48
	v_readlane_b32 s22, v246, 49
	v_readlane_b32 s23, v246, 50
	v_readlane_b32 s24, v246, 51
	v_readlane_b32 s25, v246, 52
	v_readlane_b32 s26, v246, 53
	v_readlane_b32 s27, v246, 54
	s_mov_b64 exec, s[92:93]
	s_waitcnt vmcnt(11)
	v_lshlrev_b32_e32 v76, 16, v68
	v_and_b32_e32 v77, 0xffff0000, v68
	v_lshlrev_b32_e32 v68, 16, v69
	v_and_b32_e32 v69, 0xffff0000, v69
	s_waitcnt vmcnt(10)
	v_lshlrev_b32_e32 v78, 16, v70
	v_and_b32_e32 v79, 0xffff0000, v70
	v_lshlrev_b32_e32 v70, 16, v71
	v_and_b32_e32 v71, 0xffff0000, v71
	v_pk_add_f32 v[68:69], v[68:69], v[70:71]
	v_pk_add_f32 v[70:71], v[76:77], v[78:79]
	v_mov_b32_e32 v79, v69
	v_pk_mov_b32 v[76:77], v[70:71], v[68:69] op_sel:[1,0]
	v_mov_b32_e32 v78, v70
	v_pk_add_f32 v[76:77], v[76:77], v[78:79]
	s_nop 0
	v_add_f32_e32 v42, v76, v77
	ds_bpermute_b32 v49, v11, v42
	s_waitcnt lgkmcnt(0)
	v_add_f32_e32 v42, v42, v49
	ds_bpermute_b32 v49, v12, v42
	s_waitcnt lgkmcnt(0)
	v_add_f32_e32 v42, v42, v49
	ds_bpermute_b32 v49, v13, v42
	s_waitcnt lgkmcnt(0)
	v_add_f32_e32 v42, v42, v49
	ds_bpermute_b32 v57, v14, v42
	v_mov_b32_e32 v49, v43
	v_lshlrev_b64 v[48:49], 12, v[48:49]
	v_lshl_add_u64 v[48:49], s[70:71], 0, v[48:49]
	v_lshl_add_u64 v[48:49], v[48:49], 0, v[66:67]
	s_waitcnt lgkmcnt(0)
	v_add_f32_e32 v42, v42, v57
	v_fmamk_f32 v71, v42, 0xbc800000, v71
	v_fmac_f32_e32 v70, 0xbc800000, v42
	v_fmamk_f32 v69, v42, 0xbc800000, v69
	v_fmac_f32_e32 v68, 0xbc800000, v42
	v_pk_mul_f32 v[76:77], v[68:69], v[68:69]
	v_pk_mul_f32 v[78:79], v[70:71], v[70:71]
	v_add_co_u32_e32 v48, vcc, 0x6700000, v48
	v_pk_mov_b32 v[80:81], v[78:79], v[76:77] op_sel:[1,0]
	v_mov_b32_e32 v79, v77
	v_pk_add_f32 v[76:77], v[80:81], v[78:79]
	v_addc_co_u32_e32 v49, vcc, 0, v49, vcc
	v_add_f32_e32 v42, v76, v77
	ds_bpermute_b32 v57, v11, v42
	s_waitcnt vmcnt(9)
	v_lshlrev_b32_e32 v66, 16, v72
	v_and_b32_e32 v67, 0xffff0000, v72
	v_lshlrev_b32_e32 v72, 16, v73
	v_and_b32_e32 v73, 0xffff0000, v73
	s_waitcnt lgkmcnt(0)
	v_add_f32_e32 v42, v42, v57
	ds_bpermute_b32 v57, v12, v42
	s_waitcnt vmcnt(8)
	v_lshlrev_b32_e32 v76, 16, v74
	v_and_b32_e32 v77, 0xffff0000, v74
	v_lshlrev_b32_e32 v74, 16, v75
	v_and_b32_e32 v75, 0xffff0000, v75
	s_waitcnt lgkmcnt(0)
	v_add_f32_e32 v42, v42, v57
	ds_bpermute_b32 v57, v13, v42
	s_waitcnt lgkmcnt(0)
	v_add_f32_e32 v42, v42, v57
	ds_bpermute_b32 v57, v14, v42
	s_waitcnt lgkmcnt(0)
	v_add_f32_e32 v42, v42, v57
	v_fmamk_f32 v42, v42, 0x3c800000, v16
	v_mul_f32_e32 v57, 0x4b800000, v42
	v_cmp_gt_f32_e32 vcc, s31, v42
	s_nop 1
	v_cndmask_b32_e32 v42, v42, v57, vcc
	v_rsq_f32_e32 v42, v42
	s_nop 0
	v_mul_f32_e32 v57, 0x45800000, v42
	v_cndmask_b32_e32 v42, v42, v57, vcc
	v_pk_mul_f32 v[70:71], v[70:71], v[42:43] op_sel_hi:[1,0]
	v_pk_mul_f32 v[68:69], v[68:69], v[42:43] op_sel_hi:[1,0]
	s_waitcnt vmcnt(6)
	v_pk_fma_f32 v[58:59], v[58:59], v[70:71], v[62:63]
	v_pk_fma_f32 v[60:61], v[60:61], v[68:69], v[64:65]
	v_pk_add_f32 v[58:59], v[58:59], v[66:67]
	v_pk_add_f32 v[60:61], v[60:61], v[72:73]
	v_pk_mul_f32 v[58:59], v[58:59], v[76:77]
	v_pk_mul_f32 v[60:61], v[60:61], v[74:75]
	v_bfe_u32 v42, v58, 16, 1
	v_bfe_u32 v62, v60, 16, 1
	v_bfe_u32 v57, v59, 16, 1
	v_bfe_u32 v63, v61, 16, 1
	v_add3_u32 v42, v58, v42, s33
	v_add3_u32 v58, v60, v62, s33
	v_add3_u32 v57, v59, v57, s33
	v_add3_u32 v59, v61, v63, s33
	v_lshrrev_b32_e32 v42, 16, v42
	v_lshrrev_b32_e32 v60, 16, v58
	v_and_or_b32 v58, v57, s30, v42
	v_and_or_b32 v59, v59, s30, v60
	global_store_dwordx2 v[48:49], v[58:59], off offset:1024
	s_mov_b64 exec, s[94:95]
	s_branch .Lpo5_loopx
; __device__ __forceinline__ unsigned pk2(float lo, float hi) { return f2bf(lo) | (f2bf(hi) << 16); }
; __device__ __forceinline__ f32x4 bf4(u32x2 w) { return (f32x4){bflo(w.x), bfhi(w.x), bflo(w.y), bfhi(w.y)}; }
; __device__ __forceinline__ void rwkv_out_phase(int nrows, const bf16* Y, const bf16* G, const bf16* BV, const float* gng, const float* gnb, bf16* CC, int tid) {
;     ...
;         f32x4 y = y0 + y1;
;         float sm = (y.x + y.y) + (y.z + y.w);
; #pragma unroll
;         for (int o = 1; o < 16; o <<= 1) sm += __shfl_xor(sm, o);
;         const float mu = sm * (1.f / 64.f); y = y - mu;
;         float s2 = (y.x * y.x + y.y * y.y) + (y.z * y.z + y.w * y.w);
; #pragma unroll
;         for (int o = 1; o < 16; o <<= 1) s2 += __shfl_xor(s2, o);
;         const float rstd = rsqrtf(s2 * (1.f / 64.f) + GN_EPS);
;         const f32x4 gg = *(const f32x4*)(gng + c), gb = *(const f32x4*)(gnb + c);
;         const f32x4 bv = bf4(*(const u32x2*)(BV + (size_t)m * BW + c)), gt = bf4(*(const u32x2*)(G + (size_t)m * BW + c));
;         const f32x4 o = (y * rstd * gg + gb + bv) * gt;
;         u32x2 w; w.x = pk2(o.x, o.y); w.y = pk2(o.z, o.w);
;         *(u32x2*)(CC + (size_t)m * D + 512 + c) = w;
.Lpo5_drainx:
	s_mov_b64 exec, s[92:93]
	s_waitcnt vmcnt(5)
	v_lshlrev_b32_e32 v36, 16, v28
	v_and_b32_e32 v37, 0xffff0000, v28
	v_lshlrev_b32_e32 v28, 16, v29
	v_and_b32_e32 v29, 0xffff0000, v29
	s_waitcnt vmcnt(4)
	v_lshlrev_b32_e32 v38, 16, v30
	v_and_b32_e32 v39, 0xffff0000, v30
	v_lshlrev_b32_e32 v30, 16, v31
	v_and_b32_e32 v31, 0xffff0000, v31
	v_pk_add_f32 v[28:29], v[28:29], v[30:31]
	v_pk_add_f32 v[30:31], v[36:37], v[38:39]
	v_mov_b32_e32 v39, v29
	v_pk_mov_b32 v[36:37], v[30:31], v[28:29] op_sel:[1,0]
	v_mov_b32_e32 v38, v30
	v_pk_add_f32 v[36:37], v[36:37], v[38:39]
	s_nop 0
	v_add_f32_e32 v2, v36, v37
	ds_bpermute_b32 v9, v11, v2
	s_waitcnt lgkmcnt(0)
	v_add_f32_e32 v2, v2, v9
	ds_bpermute_b32 v9, v12, v2
	s_waitcnt lgkmcnt(0)
	v_add_f32_e32 v2, v2, v9
	ds_bpermute_b32 v9, v13, v2
	s_waitcnt lgkmcnt(0)
	v_add_f32_e32 v2, v2, v9
	ds_bpermute_b32 v17, v14, v2
	v_mov_b32_e32 v9, v3
	v_lshlrev_b64 v[8:9], 12, v[8:9]
	v_lshl_add_u64 v[8:9], s[70:71], 0, v[8:9]
	v_lshl_add_u64 v[8:9], v[8:9], 0, v[26:27]
	s_waitcnt lgkmcnt(0)
	v_add_f32_e32 v2, v2, v17
	v_fmamk_f32 v31, v2, 0xbc800000, v31
	v_fmac_f32_e32 v30, 0xbc800000, v2
	v_fmamk_f32 v29, v2, 0xbc800000, v29
	v_fmac_f32_e32 v28, 0xbc800000, v2
	v_pk_mul_f32 v[36:37], v[28:29], v[28:29]
	v_pk_mul_f32 v[38:39], v[30:31], v[30:31]
	v_add_co_u32_e32 v8, vcc, 0x6700000, v8
	v_pk_mov_b32 v[40:41], v[38:39], v[36:37] op_sel:[1,0]
	v_mov_b32_e32 v39, v37
	v_pk_add_f32 v[36:37], v[40:41], v[38:39]
	v_addc_co_u32_e32 v9, vcc, 0, v9, vcc
	v_add_f32_e32 v2, v36, v37
	ds_bpermute_b32 v17, v11, v2
	s_waitcnt vmcnt(3)
	v_lshlrev_b32_e32 v26, 16, v32
	v_and_b32_e32 v27, 0xffff0000, v32
	v_lshlrev_b32_e32 v32, 16, v33
	v_and_b32_e32 v33, 0xffff0000, v33
	s_waitcnt lgkmcnt(0)
	v_add_f32_e32 v2, v2, v17
	ds_bpermute_b32 v17, v12, v2
	s_waitcnt vmcnt(2)
	v_lshlrev_b32_e32 v36, 16, v34
	v_and_b32_e32 v37, 0xffff0000, v34
	v_lshlrev_b32_e32 v34, 16, v35
	v_and_b32_e32 v35, 0xffff0000, v35
	s_waitcnt lgkmcnt(0)
	v_add_f32_e32 v2, v2, v17
	ds_bpermute_b32 v17, v13, v2
	s_waitcnt lgkmcnt(0)
	v_add_f32_e32 v2, v2, v17
	ds_bpermute_b32 v17, v14, v2
	s_waitcnt lgkmcnt(0)
	v_add_f32_e32 v2, v2, v17
	v_fmamk_f32 v2, v2, 0x3c800000, v16
	v_mul_f32_e32 v17, 0x4b800000, v2
	v_cmp_gt_f32_e32 vcc, s31, v2
	s_nop 1
	v_cndmask_b32_e32 v2, v2, v17, vcc
	v_rsq_f32_e32 v2, v2
	s_nop 0
	v_mul_f32_e32 v17, 0x45800000, v2
	v_cndmask_b32_e32 v2, v2, v17, vcc
	v_pk_mul_f32 v[30:31], v[30:31], v[2:3] op_sel_hi:[1,0]
	v_pk_mul_f32 v[28:29], v[28:29], v[2:3] op_sel_hi:[1,0]
	s_waitcnt vmcnt(0)
	v_pk_fma_f32 v[18:19], v[18:19], v[30:31], v[22:23]
	v_pk_fma_f32 v[20:21], v[20:21], v[28:29], v[24:25]
	v_pk_add_f32 v[18:19], v[18:19], v[26:27]
	v_pk_add_f32 v[20:21], v[20:21], v[32:33]
	v_pk_mul_f32 v[18:19], v[18:19], v[36:37]
	v_pk_mul_f32 v[20:21], v[20:21], v[34:35]
	v_bfe_u32 v2, v18, 16, 1
	v_bfe_u32 v22, v20, 16, 1
	v_bfe_u32 v17, v19, 16, 1
	v_bfe_u32 v23, v21, 16, 1
	v_add3_u32 v2, v18, v2, s33
	v_add3_u32 v18, v20, v22, s33
	v_add3_u32 v17, v19, v17, s33
	v_add3_u32 v19, v21, v23, s33
	v_lshrrev_b32_e32 v2, 16, v2
	v_lshrrev_b32_e32 v20, 16, v18
	v_and_or_b32 v18, v17, s30, v2
	v_and_or_b32 v19, v19, s30, v20
	global_store_dwordx2 v[8:9], v[18:19], off offset:1024
	s_branch .LBB0_638
.Lpo5_drainy:
	s_mov_b64 exec, s[92:93]
	s_waitcnt vmcnt(5)
	v_lshlrev_b32_e32 v76, 16, v68
	v_and_b32_e32 v77, 0xffff0000, v68
	v_lshlrev_b32_e32 v68, 16, v69
	v_and_b32_e32 v69, 0xffff0000, v69
	s_waitcnt vmcnt(4)
	v_lshlrev_b32_e32 v78, 16, v70
	v_and_b32_e32 v79, 0xffff0000, v70
	v_lshlrev_b32_e32 v70, 16, v71
	v_and_b32_e32 v71, 0xffff0000, v71
	v_pk_add_f32 v[68:69], v[68:69], v[70:71]
	v_pk_add_f32 v[70:71], v[76:77], v[78:79]
	v_mov_b32_e32 v79, v69
	v_pk_mov_b32 v[76:77], v[70:71], v[68:69] op_sel:[1,0]
	v_mov_b32_e32 v78, v70
	v_pk_add_f32 v[76:77], v[76:77], v[78:79]
	s_nop 0
	v_add_f32_e32 v42, v76, v77
	ds_bpermute_b32 v49, v11, v42
	s_waitcnt lgkmcnt(0)
	v_add_f32_e32 v42, v42, v49
	ds_bpermute_b32 v49, v12, v42
	s_waitcnt lgkmcnt(0)
	v_add_f32_e32 v42, v42, v49
	ds_bpermute_b32 v49, v13, v42
	s_waitcnt lgkmcnt(0)
	v_add_f32_e32 v42, v42, v49
	ds_bpermute_b32 v57, v14, v42
	v_mov_b32_e32 v49, v43
	v_lshlrev_b64 v[48:49], 12, v[48:49]
	v_lshl_add_u64 v[48:49], s[70:71], 0, v[48:49]
	v_lshl_add_u64 v[48:49], v[48:49], 0, v[66:67]
	s_waitcnt lgkmcnt(0)
	v_add_f32_e32 v42, v42, v57
	v_fmamk_f32 v71, v42, 0xbc800000, v71
	v_fmac_f32_e32 v70, 0xbc800000, v42
	v_fmamk_f32 v69, v42, 0xbc800000, v69
	v_fmac_f32_e32 v68, 0xbc800000, v42
	v_pk_mul_f32 v[76:77], v[68:69], v[68:69]
	v_pk_mul_f32 v[78:79], v[70:71], v[70:71]
	v_add_co_u32_e32 v48, vcc, 0x6700000, v48
	v_pk_mov_b32 v[80:81], v[78:79], v[76:77] op_sel:[1,0]
	v_mov_b32_e32 v79, v77
	v_pk_add_f32 v[76:77], v[80:81], v[78:79]
	v_addc_co_u32_e32 v49, vcc, 0, v49, vcc
	v_add_f32_e32 v42, v76, v77
	ds_bpermute_b32 v57, v11, v42
	s_waitcnt vmcnt(3)
	v_lshlrev_b32_e32 v66, 16, v72
	v_and_b32_e32 v67, 0xffff0000, v72
	v_lshlrev_b32_e32 v72, 16, v73
	v_and_b32_e32 v73, 0xffff0000, v73
	s_waitcnt lgkmcnt(0)
	v_add_f32_e32 v42, v42, v57
	ds_bpermute_b32 v57, v12, v42
	s_waitcnt vmcnt(2)
	v_lshlrev_b32_e32 v76, 16, v74
	v_and_b32_e32 v77, 0xffff0000, v74
	v_lshlrev_b32_e32 v74, 16, v75
	v_and_b32_e32 v75, 0xffff0000, v75
	s_waitcnt lgkmcnt(0)
	v_add_f32_e32 v42, v42, v57
	ds_bpermute_b32 v57, v13, v42
	s_waitcnt lgkmcnt(0)
	v_add_f32_e32 v42, v42, v57
	ds_bpermute_b32 v57, v14, v42
	s_waitcnt lgkmcnt(0)
	v_add_f32_e32 v42, v42, v57
	v_fmamk_f32 v42, v42, 0x3c800000, v16
	v_mul_f32_e32 v57, 0x4b800000, v42
	v_cmp_gt_f32_e32 vcc, s31, v42
	s_nop 1
	v_cndmask_b32_e32 v42, v42, v57, vcc
	v_rsq_f32_e32 v42, v42
	s_nop 0
	v_mul_f32_e32 v57, 0x45800000, v42
	v_cndmask_b32_e32 v42, v42, v57, vcc
	v_pk_mul_f32 v[70:71], v[70:71], v[42:43] op_sel_hi:[1,0]
	v_pk_mul_f32 v[68:69], v[68:69], v[42:43] op_sel_hi:[1,0]
	s_waitcnt vmcnt(0)
	v_pk_fma_f32 v[58:59], v[58:59], v[70:71], v[62:63]
	v_pk_fma_f32 v[60:61], v[60:61], v[68:69], v[64:65]
	v_pk_add_f32 v[58:59], v[58:59], v[66:67]
	v_pk_add_f32 v[60:61], v[60:61], v[72:73]
	v_pk_mul_f32 v[58:59], v[58:59], v[76:77]
	v_pk_mul_f32 v[60:61], v[60:61], v[74:75]
	v_bfe_u32 v42, v58, 16, 1
	v_bfe_u32 v62, v60, 16, 1
	v_bfe_u32 v57, v59, 16, 1
	v_bfe_u32 v63, v61, 16, 1
	v_add3_u32 v42, v58, v42, s33
	v_add3_u32 v58, v60, v62, s33
	v_add3_u32 v57, v59, v57, s33
	v_add3_u32 v59, v61, v63, s33
	v_lshrrev_b32_e32 v42, 16, v42
	v_lshrrev_b32_e32 v60, 16, v58
	v_and_or_b32 v58, v57, s30, v42
	v_and_or_b32 v59, v59, s30, v60
	global_store_dwordx2 v[48:49], v[58:59], off offset:1024
